# out-proj epilogue rewritten without LDS transposes: 32 dwordx2 residual loads issued up front in MFMA layout, per-quad add and dwordx4 store straight from the accumulators (half-line stores)
# baseline (speedup 1.0000x reference)
; #define LAS __attribute__((address_space(3)))
; #define NTLD(p) __builtin_nontemporal_load(p)
;     __device__ __forceinline__ void operator()(const f32x4 (&acc)[2][2][4][2], const pg8::Unit& u, int wr, int wc, int fr, int fq) const {
;         asm volatile("" : "+v"(fr), "+v"(fq));
;         const int pm = u.pm; const bool sample = pm >= (MP / 256);
;         const bf16* xb = xbf + (size_t)pm * 256 * DM;
;         float* ob = sample ? out + OUT_YS + (size_t)(pm - MP / 256) * 256 * DM : out + OUT_YP + (size_t)pm * 256 * DM;
;         LAS unsigned char* T = stg + (wr * 4 + wc) * 2048;
;         const int lane = fr + 16 * fq, rr = lane >> 3, p = lane & 7;
;         const int woff0 = fr * 128 + ((fq ^ (fr & 7)) << 4), woff1 = fr * 128 + (((4 + fq) ^ (fr & 7)) << 4);
;         const int roff = rr * 128 + ((p ^ rr) << 4);
;         const int cb = 256 * u.pn + 32 * wc + 4 * p;
; #pragma unroll
;         for (int ai = 0; ai < 2; ++ai) {
;             v4u xv[4][2][2];
; #pragma unroll
;             for (int m = 0; m < 4; ++m) {
;                 const size_t ro = (size_t)(128 * ai + 64 * wr + 16 * m + rr) * DM + (cb & ~7);
; #pragma unroll
;                 for (int bj = 0; bj < 2; ++bj) { xv[m][bj][0] = NTLD((const v4u*)(xb + ro + 128 * bj)); xv[m][bj][1] = NTLD((const v4u*)(xb + ro + 8 * DM + 128 * bj)); }
;             }
; #pragma unroll
;             for (int m = 0; m < 4; ++m) {
;                 const size_t ro = (size_t)(128 * ai + 64 * wr + 16 * m + rr) * DM + cb;
; #pragma unroll
;                 for (int bj = 0; bj < 2; ++bj) {
;                     *(LAS f32x4*)(T + woff0) = acc[ai][bj][m][0]; *(LAS f32x4*)(T + woff1) = acc[ai][bj][m][1];
;                     const f32x4 a0 = *(const LAS f32x4*)(T + roff), a1 = *(const LAS f32x4*)(T + roff + 1024);
;                     const v4u t0 = xv[m][bj][0], t1 = xv[m][bj][1];
;                     const unsigned u0 = (p & 1) ? t0.z : t0.x, u1 = (p & 1) ? t0.w : t0.y, u2 = (p & 1) ? t1.z : t1.x, u3 = (p & 1) ? t1.w : t1.y;
;                     *(f32x4*)(ob + ro + 128 * bj) = (f32x4){bflo(u0), bfhi(u0), bflo(u1), bfhi(u1)} + a0; *(f32x4*)(ob + ro + 8 * DM + 128 * bj) = (f32x4){bflo(u2), bfhi(u2), bflo(u3), bfhi(u3)} + a1;
;                 }
.LBB0_1239:
	s_lshl_b32 s64, s4, 19
	s_add_u32 s60, s41, s64
	s_addc_u32 s61, s42, 0
	s_lshl_b32 s64, s4, 20
	s_add_u32 s62, s56, s64
	s_addc_u32 s63, s57, 0
	s_lshl_b32 s65, s58, 8
	s_add_i32 s65, s65, s44
	v_lshl_add_u32 v212, v173, 2, s65
	v_add_u32_e32 v213, s43, v172
	v_lshlrev_b32_e32 v210, 11, v213
	v_lshl_add_u32 v210, v212, 1, v210
	v_lshlrev_b32_e32 v211, 12, v213
	v_lshl_add_u32 v211, v212, 2, v211
	global_load_dwordx2 v[128:129], v210, s[60:61] nt
	global_load_dwordx2 v[130:131], v210, s[60:61] offset:32 nt
	global_load_dwordx2 v[132:133], v210, s[60:61] offset:256 nt
	global_load_dwordx2 v[134:135], v210, s[60:61] offset:288 nt
	s_add_u32 s60, s60, 0x8000
	s_addc_u32 s61, s61, 0
	global_load_dwordx2 v[136:137], v210, s[60:61] nt
	global_load_dwordx2 v[138:139], v210, s[60:61] offset:32 nt
	global_load_dwordx2 v[140:141], v210, s[60:61] offset:256 nt
	global_load_dwordx2 v[142:143], v210, s[60:61] offset:288 nt
	s_add_u32 s60, s60, 0x8000
	s_addc_u32 s61, s61, 0
	global_load_dwordx2 v[144:145], v210, s[60:61] nt
	global_load_dwordx2 v[146:147], v210, s[60:61] offset:32 nt
	global_load_dwordx2 v[148:149], v210, s[60:61] offset:256 nt
	global_load_dwordx2 v[150:151], v210, s[60:61] offset:288 nt
	s_add_u32 s60, s60, 0x8000
	s_addc_u32 s61, s61, 0
	global_load_dwordx2 v[164:165], v210, s[60:61] nt
	global_load_dwordx2 v[166:167], v210, s[60:61] offset:32 nt
	global_load_dwordx2 v[168:169], v210, s[60:61] offset:256 nt
	global_load_dwordx2 v[170:171], v210, s[60:61] offset:288 nt
	s_add_u32 s60, s60, 0x28000
	s_addc_u32 s61, s61, 0
	global_load_dwordx2 v[178:179], v210, s[60:61] nt
	global_load_dwordx2 v[180:181], v210, s[60:61] offset:32 nt
	global_load_dwordx2 v[182:183], v210, s[60:61] offset:256 nt
	global_load_dwordx2 v[184:185], v210, s[60:61] offset:288 nt
	s_add_u32 s60, s60, 0x8000
	s_addc_u32 s61, s61, 0
	global_load_dwordx2 v[186:187], v210, s[60:61] nt
	global_load_dwordx2 v[188:189], v210, s[60:61] offset:32 nt
	global_load_dwordx2 v[190:191], v210, s[60:61] offset:256 nt
	global_load_dwordx2 v[192:193], v210, s[60:61] offset:288 nt
	s_add_u32 s60, s60, 0x8000
	s_addc_u32 s61, s61, 0
	global_load_dwordx2 v[194:195], v210, s[60:61] nt
	global_load_dwordx2 v[196:197], v210, s[60:61] offset:32 nt
	global_load_dwordx2 v[198:199], v210, s[60:61] offset:256 nt
	global_load_dwordx2 v[200:201], v210, s[60:61] offset:288 nt
	s_add_u32 s60, s60, 0x8000
	s_addc_u32 s61, s61, 0
	global_load_dwordx2 v[202:203], v210, s[60:61] nt
	global_load_dwordx2 v[204:205], v210, s[60:61] offset:32 nt
	global_load_dwordx2 v[206:207], v210, s[60:61] offset:256 nt
	global_load_dwordx2 v[208:209], v210, s[60:61] offset:288 nt
	s_waitcnt vmcnt(31)
	v_lshlrev_b32_e32 v212, 16, v128
	v_and_b32_e32 v213, 0xffff0000, v128
	v_lshlrev_b32_e32 v214, 16, v129
	v_and_b32_e32 v215, 0xffff0000, v129
	v_add_f32_e32 v124, v124, v212
	v_add_f32_e32 v125, v125, v213
	v_add_f32_e32 v126, v126, v214
	v_add_f32_e32 v127, v127, v215
	global_store_dwordx4 v211, v[124:127], s[62:63]
	s_waitcnt vmcnt(31)
	v_lshlrev_b32_e32 v212, 16, v130
	v_and_b32_e32 v213, 0xffff0000, v130
	v_lshlrev_b32_e32 v214, 16, v131
	v_and_b32_e32 v215, 0xffff0000, v131
	v_add_f32_e32 v120, v120, v212
	v_add_f32_e32 v121, v121, v213
	v_add_f32_e32 v122, v122, v214
	v_add_f32_e32 v123, v123, v215
	global_store_dwordx4 v211, v[120:123], s[62:63] offset:64
	s_waitcnt vmcnt(31)
	v_lshlrev_b32_e32 v212, 16, v132
	v_and_b32_e32 v213, 0xffff0000, v132
	v_lshlrev_b32_e32 v214, 16, v133
	v_and_b32_e32 v215, 0xffff0000, v133
	v_add_f32_e32 v116, v116, v212
	v_add_f32_e32 v117, v117, v213
	v_add_f32_e32 v118, v118, v214
	v_add_f32_e32 v119, v119, v215
	global_store_dwordx4 v211, v[116:119], s[62:63] offset:512
	s_waitcnt vmcnt(31)
	v_lshlrev_b32_e32 v212, 16, v134
	v_and_b32_e32 v213, 0xffff0000, v134
	v_lshlrev_b32_e32 v214, 16, v135
	v_and_b32_e32 v215, 0xffff0000, v135
	v_add_f32_e32 v112, v112, v212
	v_add_f32_e32 v113, v113, v213
	v_add_f32_e32 v114, v114, v214
	v_add_f32_e32 v115, v115, v215
	global_store_dwordx4 v211, v[112:115], s[62:63] offset:576
	s_add_u32 s62, s62, 0x10000
	s_addc_u32 s63, s63, 0
	s_waitcnt vmcnt(31)
	v_lshlrev_b32_e32 v212, 16, v136
	v_and_b32_e32 v213, 0xffff0000, v136
	v_lshlrev_b32_e32 v214, 16, v137
	v_and_b32_e32 v215, 0xffff0000, v137
	v_add_f32_e32 v108, v108, v212
	v_add_f32_e32 v109, v109, v213
	v_add_f32_e32 v110, v110, v214
	v_add_f32_e32 v111, v111, v215
	global_store_dwordx4 v211, v[108:111], s[62:63]
	s_waitcnt vmcnt(31)
	v_lshlrev_b32_e32 v212, 16, v138
	v_and_b32_e32 v213, 0xffff0000, v138
	v_lshlrev_b32_e32 v214, 16, v139
	v_and_b32_e32 v215, 0xffff0000, v139
	v_add_f32_e32 v104, v104, v212
	v_add_f32_e32 v105, v105, v213
	v_add_f32_e32 v106, v106, v214
	v_add_f32_e32 v107, v107, v215
	global_store_dwordx4 v211, v[104:107], s[62:63] offset:64
	s_waitcnt vmcnt(31)
	v_lshlrev_b32_e32 v212, 16, v140
	v_and_b32_e32 v213, 0xffff0000, v140
	v_lshlrev_b32_e32 v214, 16, v141
	v_and_b32_e32 v215, 0xffff0000, v141
	v_add_f32_e32 v100, v100, v212
	v_add_f32_e32 v101, v101, v213
	v_add_f32_e32 v102, v102, v214
	v_add_f32_e32 v103, v103, v215
	global_store_dwordx4 v211, v[100:103], s[62:63] offset:512
	s_waitcnt vmcnt(31)
	v_lshlrev_b32_e32 v212, 16, v142
	v_and_b32_e32 v213, 0xffff0000, v142
	v_lshlrev_b32_e32 v214, 16, v143
	v_and_b32_e32 v215, 0xffff0000, v143
	v_add_f32_e32 v96, v96, v212
	v_add_f32_e32 v97, v97, v213
	v_add_f32_e32 v98, v98, v214
	v_add_f32_e32 v99, v99, v215
	global_store_dwordx4 v211, v[96:99], s[62:63] offset:576
	s_add_u32 s62, s62, 0x10000
	s_addc_u32 s63, s63, 0
	s_waitcnt vmcnt(31)
; #define LAS __attribute__((address_space(3)))
;     __device__ __forceinline__ void operator()(const f32x4 (&acc)[2][2][4][2], const pg8::Unit& u, int wr, int wc, int fr, int fq) const {
;     ...
;             for (int m = 0; m < 4; ++m) {
;                 const size_t ro = (size_t)(128 * ai + 64 * wr + 16 * m + rr) * DM + cb;
; #pragma unroll
;                 for (int bj = 0; bj < 2; ++bj) {
;                     *(LAS f32x4*)(T + woff0) = acc[ai][bj][m][0]; *(LAS f32x4*)(T + woff1) = acc[ai][bj][m][1];
;                     const f32x4 a0 = *(const LAS f32x4*)(T + roff), a1 = *(const LAS f32x4*)(T + roff + 1024);
;                     const v4u t0 = xv[m][bj][0], t1 = xv[m][bj][1];
;                     const unsigned u0 = (p & 1) ? t0.z : t0.x, u1 = (p & 1) ? t0.w : t0.y, u2 = (p & 1) ? t1.z : t1.x, u3 = (p & 1) ? t1.w : t1.y;
;                     *(f32x4*)(ob + ro + 128 * bj) = (f32x4){bflo(u0), bfhi(u0), bflo(u1), bfhi(u1)} + a0; *(f32x4*)(ob + ro + 8 * DM + 128 * bj) = (f32x4){bflo(u2), bfhi(u2), bflo(u3), bfhi(u3)} + a1;
;                 }
	v_lshlrev_b32_e32 v212, 16, v144
	v_and_b32_e32 v213, 0xffff0000, v144
	v_lshlrev_b32_e32 v214, 16, v145
	v_and_b32_e32 v215, 0xffff0000, v145
	v_add_f32_e32 v92, v92, v212
	v_add_f32_e32 v93, v93, v213
	v_add_f32_e32 v94, v94, v214
	v_add_f32_e32 v95, v95, v215
	global_store_dwordx4 v211, v[92:95], s[62:63]
	s_waitcnt vmcnt(31)
	v_lshlrev_b32_e32 v212, 16, v146
	v_and_b32_e32 v213, 0xffff0000, v146
	v_lshlrev_b32_e32 v214, 16, v147
	v_and_b32_e32 v215, 0xffff0000, v147
	v_add_f32_e32 v88, v88, v212
	v_add_f32_e32 v89, v89, v213
	v_add_f32_e32 v90, v90, v214
	v_add_f32_e32 v91, v91, v215
	global_store_dwordx4 v211, v[88:91], s[62:63] offset:64
	s_waitcnt vmcnt(31)
	v_lshlrev_b32_e32 v212, 16, v148
	v_and_b32_e32 v213, 0xffff0000, v148
	v_lshlrev_b32_e32 v214, 16, v149
	v_and_b32_e32 v215, 0xffff0000, v149
	v_add_f32_e32 v84, v84, v212
	v_add_f32_e32 v85, v85, v213
	v_add_f32_e32 v86, v86, v214
	v_add_f32_e32 v87, v87, v215
	global_store_dwordx4 v211, v[84:87], s[62:63] offset:512
	s_waitcnt vmcnt(31)
	v_lshlrev_b32_e32 v212, 16, v150
	v_and_b32_e32 v213, 0xffff0000, v150
	v_lshlrev_b32_e32 v214, 16, v151
	v_and_b32_e32 v215, 0xffff0000, v151
	v_add_f32_e32 v80, v80, v212
	v_add_f32_e32 v81, v81, v213
	v_add_f32_e32 v82, v82, v214
	v_add_f32_e32 v83, v83, v215
	global_store_dwordx4 v211, v[80:83], s[62:63] offset:576
	s_add_u32 s62, s62, 0x10000
	s_addc_u32 s63, s63, 0
	s_waitcnt vmcnt(31)
	v_lshlrev_b32_e32 v212, 16, v164
	v_and_b32_e32 v213, 0xffff0000, v164
	v_lshlrev_b32_e32 v214, 16, v165
	v_and_b32_e32 v215, 0xffff0000, v165
	v_add_f32_e32 v76, v76, v212
	v_add_f32_e32 v77, v77, v213
	v_add_f32_e32 v78, v78, v214
	v_add_f32_e32 v79, v79, v215
	global_store_dwordx4 v211, v[76:79], s[62:63]
	s_waitcnt vmcnt(31)
	v_lshlrev_b32_e32 v212, 16, v166
	v_and_b32_e32 v213, 0xffff0000, v166
	v_lshlrev_b32_e32 v214, 16, v167
	v_and_b32_e32 v215, 0xffff0000, v167
	v_add_f32_e32 v72, v72, v212
	v_add_f32_e32 v73, v73, v213
	v_add_f32_e32 v74, v74, v214
	v_add_f32_e32 v75, v75, v215
	global_store_dwordx4 v211, v[72:75], s[62:63] offset:64
	s_waitcnt vmcnt(31)
	v_lshlrev_b32_e32 v212, 16, v168
	v_and_b32_e32 v213, 0xffff0000, v168
	v_lshlrev_b32_e32 v214, 16, v169
	v_and_b32_e32 v215, 0xffff0000, v169
	v_add_f32_e32 v68, v68, v212
	v_add_f32_e32 v69, v69, v213
	v_add_f32_e32 v70, v70, v214
	v_add_f32_e32 v71, v71, v215
	global_store_dwordx4 v211, v[68:71], s[62:63] offset:512
	s_waitcnt vmcnt(31)
	v_lshlrev_b32_e32 v212, 16, v170
	v_and_b32_e32 v213, 0xffff0000, v170
	v_lshlrev_b32_e32 v214, 16, v171
	v_and_b32_e32 v215, 0xffff0000, v171
	v_add_f32_e32 v64, v64, v212
	v_add_f32_e32 v65, v65, v213
	v_add_f32_e32 v66, v66, v214
	v_add_f32_e32 v67, v67, v215
	global_store_dwordx4 v211, v[64:67], s[62:63] offset:576
	s_add_u32 s62, s62, 0x50000
	s_addc_u32 s63, s63, 0
	s_waitcnt vmcnt(31)
	v_lshlrev_b32_e32 v212, 16, v178
	v_and_b32_e32 v213, 0xffff0000, v178
	v_lshlrev_b32_e32 v214, 16, v179
	v_and_b32_e32 v215, 0xffff0000, v179
	v_add_f32_e32 v60, v60, v212
	v_add_f32_e32 v61, v61, v213
	v_add_f32_e32 v62, v62, v214
	v_add_f32_e32 v63, v63, v215
	global_store_dwordx4 v211, v[60:63], s[62:63]
	s_waitcnt vmcnt(31)
	v_lshlrev_b32_e32 v212, 16, v180
	v_and_b32_e32 v213, 0xffff0000, v180
	v_lshlrev_b32_e32 v214, 16, v181
	v_and_b32_e32 v215, 0xffff0000, v181
	v_add_f32_e32 v56, v56, v212
	v_add_f32_e32 v57, v57, v213
	v_add_f32_e32 v58, v58, v214
	v_add_f32_e32 v59, v59, v215
	global_store_dwordx4 v211, v[56:59], s[62:63] offset:64
	s_waitcnt vmcnt(31)
	v_lshlrev_b32_e32 v212, 16, v182
	v_and_b32_e32 v213, 0xffff0000, v182
	v_lshlrev_b32_e32 v214, 16, v183
	v_and_b32_e32 v215, 0xffff0000, v183
	v_add_f32_e32 v52, v52, v212
	v_add_f32_e32 v53, v53, v213
	v_add_f32_e32 v54, v54, v214
	v_add_f32_e32 v55, v55, v215
	global_store_dwordx4 v211, v[52:55], s[62:63] offset:512
	s_waitcnt vmcnt(31)
	v_lshlrev_b32_e32 v212, 16, v184
	v_and_b32_e32 v213, 0xffff0000, v184
	v_lshlrev_b32_e32 v214, 16, v185
	v_and_b32_e32 v215, 0xffff0000, v185
	v_add_f32_e32 v48, v48, v212
	v_add_f32_e32 v49, v49, v213
	v_add_f32_e32 v50, v50, v214
	v_add_f32_e32 v51, v51, v215
	global_store_dwordx4 v211, v[48:51], s[62:63] offset:576
	s_add_u32 s62, s62, 0x10000
	s_addc_u32 s63, s63, 0
	s_waitcnt vmcnt(31)
; #define PG8_BAR __builtin_amdgcn_s_barrier()
; #define LAS __attribute__((address_space(3)))
; template <class Epi, class Sched, bool ALIGN_EPI = false, bool SP2 = false>
; __device__ __forceinline__ void gemm_phase(PG8_LAS unsigned char* lds, const Gemm g, const Sched& S, const Epi& E) {
;     ...
;         if constexpr (ALIGN_EPI) { if (wr == 0) PG8_BAR; }
;         if constexpr (!Epi::AFTER_DRAIN) { E(acc, cur, wr, wc, fr, fq); S.done(cur); }
;         if (!has_next) break;
; #pragma unroll
;         for (int a = 0; a < 2; ++a)
; #pragma unroll
;             for (int b = 0; b < 2; ++b)
; #pragma unroll
;                 for (int m = 0; m < 4; ++m)
; #pragma unroll
;                     for (int n = 0; n < 2; ++n) acc[a][b][m][n] = (f32x4){0.f, 0.f, 0.f, 0.f};
;         cur = nxt; cA = nA; cB = nB; ++ui;
;         if constexpr (ALIGN_EPI) { if (wr == 1) PG8_BAR; }
;     }
;     __device__ __forceinline__ void operator()(const f32x4 (&acc)[2][2][4][2], const pg8::Unit& u, int wr, int wc, int fr, int fq) const {
;     ...
;             for (int m = 0; m < 4; ++m) {
;                 const size_t ro = (size_t)(128 * ai + 64 * wr + 16 * m + rr) * DM + cb;
; #pragma unroll
;                 for (int bj = 0; bj < 2; ++bj) {
;                     *(LAS f32x4*)(T + woff0) = acc[ai][bj][m][0]; *(LAS f32x4*)(T + woff1) = acc[ai][bj][m][1];
;                     const f32x4 a0 = *(const LAS f32x4*)(T + roff), a1 = *(const LAS f32x4*)(T + roff + 1024);
;                     const v4u t0 = xv[m][bj][0], t1 = xv[m][bj][1];
;                     const unsigned u0 = (p & 1) ? t0.z : t0.x, u1 = (p & 1) ? t0.w : t0.y, u2 = (p & 1) ? t1.z : t1.x, u3 = (p & 1) ? t1.w : t1.y;
;                     *(f32x4*)(ob + ro + 128 * bj) = (f32x4){bflo(u0), bfhi(u0), bflo(u1), bfhi(u1)} + a0; *(f32x4*)(ob + ro + 8 * DM + 128 * bj) = (f32x4){bflo(u2), bfhi(u2), bflo(u3), bfhi(u3)} + a1;
;                 }
	v_lshlrev_b32_e32 v212, 16, v186
	v_and_b32_e32 v213, 0xffff0000, v186
	v_lshlrev_b32_e32 v214, 16, v187
	v_and_b32_e32 v215, 0xffff0000, v187
	v_add_f32_e32 v44, v44, v212
	v_add_f32_e32 v45, v45, v213
	v_add_f32_e32 v46, v46, v214
	v_add_f32_e32 v47, v47, v215
	global_store_dwordx4 v211, v[44:47], s[62:63]
	s_waitcnt vmcnt(31)
	v_lshlrev_b32_e32 v212, 16, v188
	v_and_b32_e32 v213, 0xffff0000, v188
	v_lshlrev_b32_e32 v214, 16, v189
	v_and_b32_e32 v215, 0xffff0000, v189
	v_add_f32_e32 v40, v40, v212
	v_add_f32_e32 v41, v41, v213
	v_add_f32_e32 v42, v42, v214
	v_add_f32_e32 v43, v43, v215
	global_store_dwordx4 v211, v[40:43], s[62:63] offset:64
	s_waitcnt vmcnt(31)
	v_lshlrev_b32_e32 v212, 16, v190
	v_and_b32_e32 v213, 0xffff0000, v190
	v_lshlrev_b32_e32 v214, 16, v191
	v_and_b32_e32 v215, 0xffff0000, v191
	v_add_f32_e32 v36, v36, v212
	v_add_f32_e32 v37, v37, v213
	v_add_f32_e32 v38, v38, v214
	v_add_f32_e32 v39, v39, v215
	global_store_dwordx4 v211, v[36:39], s[62:63] offset:512
	s_waitcnt vmcnt(31)
	v_lshlrev_b32_e32 v212, 16, v192
	v_and_b32_e32 v213, 0xffff0000, v192
	v_lshlrev_b32_e32 v214, 16, v193
	v_and_b32_e32 v215, 0xffff0000, v193
	v_add_f32_e32 v32, v32, v212
	v_add_f32_e32 v33, v33, v213
	v_add_f32_e32 v34, v34, v214
	v_add_f32_e32 v35, v35, v215
	global_store_dwordx4 v211, v[32:35], s[62:63] offset:576
	s_add_u32 s62, s62, 0x10000
	s_addc_u32 s63, s63, 0
	s_waitcnt vmcnt(31)
	v_lshlrev_b32_e32 v212, 16, v194
	v_and_b32_e32 v213, 0xffff0000, v194
	v_lshlrev_b32_e32 v214, 16, v195
	v_and_b32_e32 v215, 0xffff0000, v195
	v_add_f32_e32 v28, v28, v212
	v_add_f32_e32 v29, v29, v213
	v_add_f32_e32 v30, v30, v214
	v_add_f32_e32 v31, v31, v215
	global_store_dwordx4 v211, v[28:31], s[62:63]
	s_waitcnt vmcnt(31)
	v_lshlrev_b32_e32 v212, 16, v196
	v_and_b32_e32 v213, 0xffff0000, v196
	v_lshlrev_b32_e32 v214, 16, v197
	v_and_b32_e32 v215, 0xffff0000, v197
	v_add_f32_e32 v24, v24, v212
	v_add_f32_e32 v25, v25, v213
	v_add_f32_e32 v26, v26, v214
	v_add_f32_e32 v27, v27, v215
	global_store_dwordx4 v211, v[24:27], s[62:63] offset:64
	s_waitcnt vmcnt(31)
	v_lshlrev_b32_e32 v212, 16, v198
	v_and_b32_e32 v213, 0xffff0000, v198
	v_lshlrev_b32_e32 v214, 16, v199
	v_and_b32_e32 v215, 0xffff0000, v199
	v_add_f32_e32 v20, v20, v212
	v_add_f32_e32 v21, v21, v213
	v_add_f32_e32 v22, v22, v214
	v_add_f32_e32 v23, v23, v215
	global_store_dwordx4 v211, v[20:23], s[62:63] offset:512
	s_waitcnt vmcnt(31)
	v_lshlrev_b32_e32 v212, 16, v200
	v_and_b32_e32 v213, 0xffff0000, v200
	v_lshlrev_b32_e32 v214, 16, v201
	v_and_b32_e32 v215, 0xffff0000, v201
	v_add_f32_e32 v16, v16, v212
	v_add_f32_e32 v17, v17, v213
	v_add_f32_e32 v18, v18, v214
	v_add_f32_e32 v19, v19, v215
	global_store_dwordx4 v211, v[16:19], s[62:63] offset:576
	s_add_u32 s62, s62, 0x10000
	s_addc_u32 s63, s63, 0
	s_waitcnt vmcnt(31)
	v_lshlrev_b32_e32 v212, 16, v202
	v_and_b32_e32 v213, 0xffff0000, v202
	v_lshlrev_b32_e32 v214, 16, v203
	v_and_b32_e32 v215, 0xffff0000, v203
	v_add_f32_e32 v12, v12, v212
	v_add_f32_e32 v13, v13, v213
	v_add_f32_e32 v14, v14, v214
	v_add_f32_e32 v15, v15, v215
	global_store_dwordx4 v211, v[12:15], s[62:63]
	s_waitcnt vmcnt(31)
	v_lshlrev_b32_e32 v212, 16, v204
	v_and_b32_e32 v213, 0xffff0000, v204
	v_lshlrev_b32_e32 v214, 16, v205
	v_and_b32_e32 v215, 0xffff0000, v205
	v_add_f32_e32 v8, v8, v212
	v_add_f32_e32 v9, v9, v213
	v_add_f32_e32 v10, v10, v214
	v_add_f32_e32 v11, v11, v215
	global_store_dwordx4 v211, v[8:11], s[62:63] offset:64
	s_waitcnt vmcnt(31)
	v_lshlrev_b32_e32 v212, 16, v206
	v_and_b32_e32 v213, 0xffff0000, v206
	v_lshlrev_b32_e32 v214, 16, v207
	v_and_b32_e32 v215, 0xffff0000, v207
	v_add_f32_e32 v4, v4, v212
	v_add_f32_e32 v5, v5, v213
	v_add_f32_e32 v6, v6, v214
	v_add_f32_e32 v7, v7, v215
	global_store_dwordx4 v211, v[4:7], s[62:63] offset:512
	s_waitcnt vmcnt(31)
	v_lshlrev_b32_e32 v212, 16, v208
	v_and_b32_e32 v213, 0xffff0000, v208
	v_lshlrev_b32_e32 v214, 16, v209
	v_and_b32_e32 v215, 0xffff0000, v209
	v_add_f32_e32 v0, v0, v212
	v_add_f32_e32 v1, v1, v213
	v_add_f32_e32 v2, v2, v214
	v_add_f32_e32 v3, v3, v215
	global_store_dwordx4 v211, v[0:3], s[62:63] offset:576
	s_andn2_b64 vcc, exec, s[0:1]
	s_mov_b64 s[0:1], -1
	s_cbranch_vccnz .LBB0_1228
	s_andn2_b64 vcc, exec, s[8:9]
	s_cbranch_vccnz .LBB0_1227
	s_barrier
	s_branch .LBB0_1227
